# code placement check: one s_nop 0 at kernel entry shifts every loop by 4 bytes
# baseline (speedup 1.0000x reference)
; #define LAS __attribute__((address_space(3)))
; __device__ __forceinline__ void init_wave_table() {
;     extern __shared__ __attribute__((aligned(16))) unsigned char lds_raw[];
;     const unsigned hw = __builtin_amdgcn_s_getreg((5 << 11) | 4) & 63u;
;     if ((threadIdx.x & 63) == 0) { *(volatile LAS int*)(uintptr_t)(LDS_WTAB + hw * 4) = (int)(threadIdx.x >> 6); if (threadIdx.x == 0x7fffffff) lds_raw[0] = 0; }
;     if (threadIdx.x == 0) { *(volatile LAS unsigned*)(uintptr_t)(LDS_MAIN + 16) = 0u; *(volatile LAS unsigned*)(uintptr_t)(LDS_MAIN + 20) = 0u; }
;     __syncthreads();
; __global__ void __launch_bounds__(512, 2) hybrid_fwd(Args a_kernarg) {
;     cg::grid_group grid = cg::this_grid();
_Z10hybrid_fwd4Args:
	s_nop 0
	s_load_dwordx2 s[16:17], s[0:1], 0xa0
	s_add_u32 s94, s0, 0xa0
	v_and_b32_e32 v2, 63, v0
	s_mov_b32 s93, s2
	s_addc_u32 s95, s1, 0
	s_getreg_b32 s4, hwreg(HW_REG_HW_ID, 0, 6)
	v_and_b32_e32 v1, 0x3ff, v0
	v_cmp_eq_u32_e32 vcc, 0, v2
	s_and_saveexec_b64 s[2:3], vcc
	s_cbranch_execz .LBB0_2
	s_lshl_b32 s4, s4, 2
	s_and_b32 s4, s4, 0xfc
	s_add_i32 s4, s4, 0x20040
	v_lshrrev_b32_e32 v2, 6, v1
	v_mov_b32_e32 v3, s4
	ds_write_b32 v3, v2
